# scan phase: iteration-2 loads prefetched behind iteration-1 loads, chains run sequentially (stores staggered), decay computed once
# speedup vs baseline: 1.0022x; 1.0022x over previous
.LBB0_567:
	s_or_b64 exec, exec, s[0:1]
	s_add_u32 s30, s50, 0x3a00000
	v_lshl_add_u32 v64, s2, 8, v131
	s_mov_b32 s6, 0x40000
	s_addc_u32 s31, s51, 0
	v_cmp_gt_i32_e32 vcc, s6, v64
	s_waitcnt lgkmcnt(0)
	s_barrier
	s_and_saveexec_b64 s[0:1], vcc
	s_cbranch_execz .LBB0_570
	s_lshl_b32 s7, s3, 8
	s_mov_b64 s[4:5], 0
	s_mov_b32 s8, 0xc2fc0000
	v_mov_b32_e32 v65, 0x42800000
	v_mov_b32_e32 v1, 0
	v_not_b32_e32 v66, 63
	s_mov_b32 s9, 0x3f2aaaab
	v_mov_b32_e32 v67, 0x3ecc95a3
	s_mov_b32 s10, 0x3f317218
	v_mov_b32_e32 v68, 0x7fc00000
	v_mov_b32_e32 v69, 0xff800000
	s_mov_b32 s11, 0x33800000
	s_mov_b32 s12, 0x8000
	s_mov_b32 s13, 0x10000
	s_mov_b32 s14, 0x18000
	s_mov_b32 s15, 0x20000
	s_mov_b32 s18, 0x28000
	s_mov_b32 s19, 0x30000
	s_mov_b32 s20, 0x38000
	s_mov_b32 s21, 0x48000
	s_mov_b32 s22, 0x50000
	s_mov_b32 s23, 0x58000
	s_mov_b32 s24, 0x60000
	s_mov_b32 s25, 0x68000
	s_mov_b32 s26, 0x70000
	s_mov_b32 s27, 0x78000
	s_mov_b32 s28, 0x80000
	s_mov_b32 s29, 0x88000
	s_mov_b32 s33, 0x90000
	s_mov_b32 s34, 0x98000
	s_mov_b32 s35, 0xa0000
	s_mov_b32 s38, 0xa8000
	s_mov_b32 s39, 0xb0000
	s_mov_b32 s40, 0xb8000
	s_mov_b32 s41, 0xc0000
	s_mov_b32 s42, 0xc8000
	s_mov_b32 s43, 0xd0000
	s_mov_b32 s44, 0xd8000
	s_mov_b32 s45, 0xe0000
	s_mov_b32 s46, 0xe8000
	s_mov_b32 s47, 0xf0000
	s_mov_b32 s52, 0xffff0000
	s_movk_i32 s53, 0x7fff
	s_mov_b32 s54, 0x3ffff
	s_cmp_lg_u32 s3, 0x200
	s_cbranch_scc1 .LBB0_569
	s_lshr_b32 s4, s2, 5
	s_lshl_b32 s4, s4, 20
	s_add_u32 s4, s30, s4
	s_addc_u32 s5, s31, 0
	s_add_u32 s6, s4, 0x1000000
	s_addc_u32 s7, s5, 0
	v_and_b32_e32 v6, 0x1fff, v64
	v_lshlrev_b32_e32 v6, 2, v6
	global_load_dword v73, v6, s[4:5]
	v_add_u32_e32 v7, 0x8000, v6
	global_load_dword v74, v7, s[4:5]
	v_add_u32_e32 v8, 0x10000, v6
	global_load_dword v75, v8, s[4:5]
	v_add_u32_e32 v9, 0x18000, v6
	global_load_dword v76, v9, s[4:5]
	v_add_u32_e32 v10, 0x20000, v6
	global_load_dword v77, v10, s[4:5]
	v_add_u32_e32 v11, 0x28000, v6
	global_load_dword v78, v11, s[4:5]
	v_add_u32_e32 v12, 0x30000, v6
	global_load_dword v79, v12, s[4:5]
	v_add_u32_e32 v13, 0x38000, v6
	global_load_dword v80, v13, s[4:5]
	v_add_u32_e32 v14, 0x40000, v6
	global_load_dword v81, v14, s[4:5]
	v_add_u32_e32 v15, 0x48000, v6
	global_load_dword v82, v15, s[4:5]
	v_add_u32_e32 v16, 0x50000, v6
	global_load_dword v83, v16, s[4:5]
	v_add_u32_e32 v17, 0x58000, v6
	global_load_dword v84, v17, s[4:5]
	v_add_u32_e32 v18, 0x60000, v6
	global_load_dword v85, v18, s[4:5]
	v_add_u32_e32 v19, 0x68000, v6
	global_load_dword v86, v19, s[4:5]
	v_add_u32_e32 v20, 0x70000, v6
	global_load_dword v87, v20, s[4:5]
	v_add_u32_e32 v21, 0x78000, v6
	global_load_dword v88, v21, s[4:5]
	v_add_u32_e32 v22, 0x80000, v6
	global_load_dword v89, v22, s[4:5]
	v_add_u32_e32 v23, 0x88000, v6
	global_load_dword v90, v23, s[4:5]
	v_add_u32_e32 v24, 0x90000, v6
	global_load_dword v91, v24, s[4:5]
	v_add_u32_e32 v25, 0x98000, v6
	global_load_dword v92, v25, s[4:5]
	v_add_u32_e32 v26, 0xa0000, v6
	global_load_dword v93, v26, s[4:5]
	v_add_u32_e32 v27, 0xa8000, v6
	global_load_dword v94, v27, s[4:5]
	v_add_u32_e32 v28, 0xb0000, v6
	global_load_dword v95, v28, s[4:5]
	v_add_u32_e32 v29, 0xb8000, v6
	global_load_dword v96, v29, s[4:5]
	v_add_u32_e32 v30, 0xc0000, v6
	global_load_dword v97, v30, s[4:5]
	v_add_u32_e32 v31, 0xc8000, v6
	global_load_dword v98, v31, s[4:5]
	v_add_u32_e32 v32, 0xd0000, v6
	global_load_dword v99, v32, s[4:5]
	v_add_u32_e32 v33, 0xd8000, v6
	global_load_dword v100, v33, s[4:5]
	v_add_u32_e32 v34, 0xe0000, v6
	global_load_dword v101, v34, s[4:5]
	v_add_u32_e32 v35, 0xe8000, v6
	global_load_dword v102, v35, s[4:5]
	v_add_u32_e32 v36, 0xf0000, v6
	global_load_dword v103, v36, s[4:5]
	v_add_u32_e32 v37, 0xf8000, v6
	global_load_dword v38, v6, s[6:7]
	global_load_dword v39, v7, s[6:7]
	global_load_dword v40, v8, s[6:7]
	global_load_dword v41, v9, s[6:7]
	global_load_dword v42, v10, s[6:7]
	global_load_dword v43, v11, s[6:7]
	global_load_dword v44, v12, s[6:7]
	global_load_dword v45, v13, s[6:7]
	global_load_dword v46, v14, s[6:7]
	global_load_dword v47, v15, s[6:7]
	global_load_dword v48, v16, s[6:7]
	global_load_dword v49, v17, s[6:7]
	global_load_dword v50, v18, s[6:7]
	global_load_dword v51, v19, s[6:7]
	global_load_dword v52, v20, s[6:7]
	global_load_dword v53, v21, s[6:7]
	global_load_dword v54, v22, s[6:7]
	global_load_dword v55, v23, s[6:7]
	global_load_dword v56, v24, s[6:7]
	global_load_dword v57, v25, s[6:7]
	global_load_dword v58, v26, s[6:7]
	global_load_dword v59, v27, s[6:7]
	global_load_dword v60, v28, s[6:7]
	global_load_dword v61, v29, s[6:7]
	global_load_dword v62, v30, s[6:7]
	global_load_dword v63, v31, s[6:7]
	global_load_dword v113, v32, s[6:7]
	global_load_dword v114, v33, s[6:7]
	global_load_dword v115, v34, s[6:7]
	global_load_dword v116, v35, s[6:7]
	global_load_dword v117, v36, s[6:7]
	v_ashrrev_i32_e32 v2, 13, v64
	v_and_b32_e32 v4, 7, v2
	v_cvt_f32_ubyte0_e32 v4, v4
	v_sub_f32_e32 v4, 0xc0a00000, v4
	v_cmp_gt_f32_e32 vcc, s8, v4
	s_nop 1
	v_cndmask_b32_e32 v5, 0, v65, vcc
	v_cndmask_b32_e32 v72, 0, v66, vcc
	v_add_f32_e32 v0, v4, v5
	v_exp_f32_e32 v0, v0
	s_nop 1
	v_ldexp_f32 v0, v0, v72
	v_sub_f32_e32 v72, 1.0, v0
	v_add_f32_e32 v104, -1.0, v72
	v_frexp_mant_f32_e32 v105, v72
	v_sub_f32_e32 v106, v104, v72
	v_sub_f32_e64 v104, -v0, v104
	v_cvt_f64_f32_e32 v[70:71], v72
	v_frexp_exp_i32_f64_e32 v70, v[70:71]
	v_cmp_gt_f32_e32 vcc, s9, v105
	v_add_f32_e32 v71, 1.0, v106
	v_add_f32_e32 v71, v104, v71
	v_subbrev_co_u32_e32 v70, vcc, 0, v70, vcc
	v_sub_u32_e32 v104, 0, v70
	v_cvt_f32_i32_e32 v70, v70
	v_ldexp_f32 v72, v72, v104
	v_ldexp_f32 v71, v71, v104
	v_add_f32_e32 v104, -1.0, v72
	v_add_f32_e32 v105, 1.0, v72
	v_add_f32_e32 v106, 1.0, v104
	v_add_f32_e32 v107, -1.0, v105
	v_sub_f32_e32 v106, v72, v106
	v_sub_f32_e32 v72, v72, v107
	v_mul_f32_e32 v107, 0x3f317218, v70
	v_add_f32_e32 v106, v71, v106
	v_add_f32_e32 v71, v71, v72
	v_fma_f32 v72, v70, s10, -v107
	v_add_f32_e32 v108, v104, v106
	v_add_f32_e32 v109, v105, v71
	v_fmac_f32_e32 v72, 0xb102e308, v70
	v_sub_f32_e32 v70, v108, v104
	v_sub_f32_e32 v104, v109, v105
	v_rcp_f32_e32 v105, v109
	v_add_f32_e32 v110, v107, v72
	v_sub_f32_e32 v71, v71, v104
	v_sub_f32_e32 v104, v110, v107
	v_sub_f32_e32 v72, v72, v104
	v_mul_f32_e32 v104, v108, v105
	v_sub_f32_e32 v70, v106, v70
	v_mul_f32_e32 v106, v109, v104
	v_fma_f32 v107, v104, v109, -v106
	v_fmac_f32_e32 v107, v104, v71
	v_add_f32_e32 v111, v106, v107
	v_sub_f32_e32 v112, v108, v111
	v_sub_f32_e32 v106, v111, v106
	v_sub_f32_e32 v108, v108, v112
	v_sub_f32_e32 v106, v106, v107
	v_sub_f32_e32 v107, v108, v111
	v_add_f32_e32 v70, v70, v107
	v_add_f32_e32 v70, v106, v70
	v_add_f32_e32 v106, v112, v70
	v_mul_f32_e32 v107, v105, v106
	v_sub_f32_e32 v108, v112, v106
	v_mul_f32_e32 v111, v109, v107
	v_add_f32_e32 v70, v70, v108
	v_add_f32_e32 v108, v104, v107
	v_fma_f32 v109, v107, v109, -v111
	v_sub_f32_e32 v104, v108, v104
	v_fmac_f32_e32 v109, v107, v71
	v_sub_f32_e32 v71, v107, v104
	v_add_f32_e32 v104, v111, v109
	v_sub_f32_e32 v107, v104, v111
	v_sub_f32_e32 v111, v106, v104
	v_sub_f32_e32 v106, v106, v111
	v_sub_f32_e32 v104, v106, v104
	v_sub_f32_e32 v107, v107, v109
	v_add_f32_e32 v70, v70, v104
	v_add_f32_e32 v70, v107, v70
	v_add_f32_e32 v70, v111, v70
	v_mul_f32_e32 v70, v105, v70
	v_add_f32_e32 v70, v71, v70
	v_add_f32_e32 v71, v108, v70
	v_mul_f32_e32 v104, v71, v71
	v_fmamk_f32 v107, v104, 0x3e9b6dac, v67
	v_sub_f32_e32 v105, v71, v108
	v_ldexp_f32 v106, v71, 1
	v_mul_f32_e32 v71, v71, v104
	v_fmaak_f32 v104, v104, v107, 0x3f2aaada
	v_mul_f32_e32 v71, v71, v104
	v_add_f32_e32 v104, v106, v71
	v_sub_f32_e32 v70, v70, v105
	v_sub_f32_e32 v105, v104, v106
	v_ldexp_f32 v70, v70, 1
	v_sub_f32_e32 v71, v71, v105
	v_add_f32_e32 v70, v70, v71
	v_add_f32_e32 v71, v104, v70
	v_sub_f32_e32 v104, v71, v104
	v_add_f32_e32 v105, v110, v71
	v_sub_f32_e32 v70, v70, v104
	v_sub_f32_e32 v104, v105, v110
	v_sub_f32_e32 v106, v105, v104
	v_sub_f32_e32 v71, v71, v104
	v_add_f32_e32 v104, v72, v70
	v_sub_f32_e32 v106, v110, v106
	v_sub_f32_e32 v107, v104, v72
	v_add_f32_e32 v71, v71, v106
	v_sub_f32_e32 v106, v104, v107
	v_sub_f32_e32 v70, v70, v107
	v_sub_f32_e32 v72, v72, v106
	v_add_f32_e32 v71, v104, v71
	v_add_f32_e32 v70, v70, v72
	v_add_f32_e32 v72, v105, v71
	v_sub_f32_e32 v104, v72, v105
	v_sub_f32_e32 v71, v71, v104
	v_add_f32_e32 v70, v70, v71
	v_add_f32_e32 v70, v72, v70
	v_cmp_nlt_f32_e32 vcc, 1.0, v0
	s_nop 1
	v_cndmask_b32_e32 v70, v68, v70, vcc
	v_cmp_neq_f32_e32 vcc, 1.0, v0
	s_nop 1
	v_cndmask_b32_e32 v70, v69, v70, vcc
	v_cmp_gt_f32_e32 vcc, s11, v0
	s_nop 1
	v_cndmask_b32_e64 v0, v70, -v0, vcc
	v_mul_f32_e32 v0, 0x43000000, v0
	v_mul_f32_e32 v0, 0x3fb8aa3b, v0
	v_exp_f32_e32 v0, v0
	s_nop 1
	s_waitcnt vmcnt(61)
	v_lshlrev_b32_e32 v118, 16, v73
	v_and_b32_e32 v73, 0xffff0000, v73
	v_fmac_f32_e32 v118, 0, v0
	v_fmac_f32_e32 v73, 0, v0
	v_bfe_u32 v120, v118, 16, 1
	v_bfe_u32 v124, v73, 16, 1
	v_add3_u32 v120, v118, v120, s53
	v_add3_u32 v124, v73, v124, s53
	v_lshrrev_b32_e32 v120, 16, v120
	v_and_or_b32 v120, v124, s52, v120
	global_store_dword v7, v120, s[4:5]
	global_store_dword v6, v1, s[4:5]
	s_waitcnt vmcnt(62)
	v_lshlrev_b32_e32 v119, 16, v74
	v_and_b32_e32 v74, 0xffff0000, v74
	v_fmac_f32_e32 v119, v0, v118
	v_fmac_f32_e32 v74, v0, v73
	v_bfe_u32 v121, v119, 16, 1
	v_bfe_u32 v125, v74, 16, 1
	v_add3_u32 v121, v119, v121, s53
	v_add3_u32 v125, v74, v125, s53
	v_lshrrev_b32_e32 v121, 16, v121
	v_and_or_b32 v121, v125, s52, v121
	global_store_dword v8, v121, s[4:5]
	s_waitcnt vmcnt(62)
	v_lshlrev_b32_e32 v118, 16, v75
	v_and_b32_e32 v75, 0xffff0000, v75
	v_fmac_f32_e32 v118, v0, v119
	v_fmac_f32_e32 v75, v0, v74
	v_bfe_u32 v122, v118, 16, 1
	v_bfe_u32 v124, v75, 16, 1
	v_add3_u32 v122, v118, v122, s53
	v_add3_u32 v124, v75, v124, s53
	v_lshrrev_b32_e32 v122, 16, v122
	v_and_or_b32 v122, v124, s52, v122
	global_store_dword v9, v122, s[4:5]
	s_waitcnt vmcnt(62)
	v_lshlrev_b32_e32 v119, 16, v76
	v_and_b32_e32 v76, 0xffff0000, v76
	v_fmac_f32_e32 v119, v0, v118
	v_fmac_f32_e32 v76, v0, v75
	v_bfe_u32 v123, v119, 16, 1
	v_bfe_u32 v125, v76, 16, 1
	v_add3_u32 v123, v119, v123, s53
	v_add3_u32 v125, v76, v125, s53
	v_lshrrev_b32_e32 v123, 16, v123
	v_and_or_b32 v123, v125, s52, v123
	global_store_dword v10, v123, s[4:5]
	s_waitcnt vmcnt(62)
	v_lshlrev_b32_e32 v118, 16, v77
	v_and_b32_e32 v77, 0xffff0000, v77
	v_fmac_f32_e32 v118, v0, v119
	v_fmac_f32_e32 v77, v0, v76
	v_bfe_u32 v120, v118, 16, 1
	v_bfe_u32 v124, v77, 16, 1
	v_add3_u32 v120, v118, v120, s53
	v_add3_u32 v124, v77, v124, s53
	v_lshrrev_b32_e32 v120, 16, v120
	v_and_or_b32 v120, v124, s52, v120
	global_store_dword v11, v120, s[4:5]
	s_waitcnt vmcnt(62)
	v_lshlrev_b32_e32 v119, 16, v78
	v_and_b32_e32 v78, 0xffff0000, v78
	v_fmac_f32_e32 v119, v0, v118
	v_fmac_f32_e32 v78, v0, v77
	v_bfe_u32 v121, v119, 16, 1
	v_bfe_u32 v125, v78, 16, 1
	v_add3_u32 v121, v119, v121, s53
	v_add3_u32 v125, v78, v125, s53
	v_lshrrev_b32_e32 v121, 16, v121
	v_and_or_b32 v121, v125, s52, v121
	global_store_dword v12, v121, s[4:5]
	s_waitcnt vmcnt(62)
	v_lshlrev_b32_e32 v118, 16, v79
	v_and_b32_e32 v79, 0xffff0000, v79
	v_fmac_f32_e32 v118, v0, v119
	v_fmac_f32_e32 v79, v0, v78
	v_bfe_u32 v122, v118, 16, 1
	v_bfe_u32 v124, v79, 16, 1
	v_add3_u32 v122, v118, v122, s53
	v_add3_u32 v124, v79, v124, s53
	v_lshrrev_b32_e32 v122, 16, v122
	v_and_or_b32 v122, v124, s52, v122
	global_store_dword v13, v122, s[4:5]
	s_waitcnt vmcnt(62)
	v_lshlrev_b32_e32 v119, 16, v80
	v_and_b32_e32 v80, 0xffff0000, v80
	v_fmac_f32_e32 v119, v0, v118
	v_fmac_f32_e32 v80, v0, v79
	v_bfe_u32 v123, v119, 16, 1
	v_bfe_u32 v125, v80, 16, 1
	v_add3_u32 v123, v119, v123, s53
	v_add3_u32 v125, v80, v125, s53
	v_lshrrev_b32_e32 v123, 16, v123
	v_and_or_b32 v123, v125, s52, v123
	global_store_dword v14, v123, s[4:5]
	s_waitcnt vmcnt(62)
	v_lshlrev_b32_e32 v118, 16, v81
	v_and_b32_e32 v81, 0xffff0000, v81
	v_fmac_f32_e32 v118, v0, v119
	v_fmac_f32_e32 v81, v0, v80
	v_bfe_u32 v120, v118, 16, 1
	v_bfe_u32 v124, v81, 16, 1
	v_add3_u32 v120, v118, v120, s53
	v_add3_u32 v124, v81, v124, s53
	v_lshrrev_b32_e32 v120, 16, v120
	v_and_or_b32 v120, v124, s52, v120
	global_store_dword v15, v120, s[4:5]
	s_waitcnt vmcnt(62)
	v_lshlrev_b32_e32 v119, 16, v82
	v_and_b32_e32 v82, 0xffff0000, v82
	v_fmac_f32_e32 v119, v0, v118
	v_fmac_f32_e32 v82, v0, v81
	v_bfe_u32 v121, v119, 16, 1
	v_bfe_u32 v125, v82, 16, 1
	v_add3_u32 v121, v119, v121, s53
	v_add3_u32 v125, v82, v125, s53
	v_lshrrev_b32_e32 v121, 16, v121
	v_and_or_b32 v121, v125, s52, v121
	global_store_dword v16, v121, s[4:5]
	s_waitcnt vmcnt(62)
	v_lshlrev_b32_e32 v118, 16, v83
	v_and_b32_e32 v83, 0xffff0000, v83
	v_fmac_f32_e32 v118, v0, v119
	v_fmac_f32_e32 v83, v0, v82
	v_bfe_u32 v122, v118, 16, 1
	v_bfe_u32 v124, v83, 16, 1
	v_add3_u32 v122, v118, v122, s53
	v_add3_u32 v124, v83, v124, s53
	v_lshrrev_b32_e32 v122, 16, v122
	v_and_or_b32 v122, v124, s52, v122
	global_store_dword v17, v122, s[4:5]
	s_waitcnt vmcnt(62)
	v_lshlrev_b32_e32 v119, 16, v84
	v_and_b32_e32 v84, 0xffff0000, v84
	v_fmac_f32_e32 v119, v0, v118
	v_fmac_f32_e32 v84, v0, v83
	v_bfe_u32 v123, v119, 16, 1
	v_bfe_u32 v125, v84, 16, 1
	v_add3_u32 v123, v119, v123, s53
	v_add3_u32 v125, v84, v125, s53
	v_lshrrev_b32_e32 v123, 16, v123
	v_and_or_b32 v123, v125, s52, v123
	global_store_dword v18, v123, s[4:5]
	s_waitcnt vmcnt(62)
	v_lshlrev_b32_e32 v118, 16, v85
	v_and_b32_e32 v85, 0xffff0000, v85
	v_fmac_f32_e32 v118, v0, v119
	v_fmac_f32_e32 v85, v0, v84
	v_bfe_u32 v120, v118, 16, 1
	v_bfe_u32 v124, v85, 16, 1
	v_add3_u32 v120, v118, v120, s53
	v_add3_u32 v124, v85, v124, s53
	v_lshrrev_b32_e32 v120, 16, v120
	v_and_or_b32 v120, v124, s52, v120
	global_store_dword v19, v120, s[4:5]
	s_waitcnt vmcnt(62)
	v_lshlrev_b32_e32 v119, 16, v86
	v_and_b32_e32 v86, 0xffff0000, v86
	v_fmac_f32_e32 v119, v0, v118
	v_fmac_f32_e32 v86, v0, v85
	v_bfe_u32 v121, v119, 16, 1
	v_bfe_u32 v125, v86, 16, 1
	v_add3_u32 v121, v119, v121, s53
	v_add3_u32 v125, v86, v125, s53
	v_lshrrev_b32_e32 v121, 16, v121
	v_and_or_b32 v121, v125, s52, v121
	global_store_dword v20, v121, s[4:5]
	s_waitcnt vmcnt(62)
	v_lshlrev_b32_e32 v118, 16, v87
	v_and_b32_e32 v87, 0xffff0000, v87
	v_fmac_f32_e32 v118, v0, v119
	v_fmac_f32_e32 v87, v0, v86
	v_bfe_u32 v122, v118, 16, 1
	v_bfe_u32 v124, v87, 16, 1
	v_add3_u32 v122, v118, v122, s53
	v_add3_u32 v124, v87, v124, s53
	v_lshrrev_b32_e32 v122, 16, v122
	v_and_or_b32 v122, v124, s52, v122
	global_store_dword v21, v122, s[4:5]
	s_waitcnt vmcnt(62)
	v_lshlrev_b32_e32 v119, 16, v88
	v_and_b32_e32 v88, 0xffff0000, v88
	v_fmac_f32_e32 v119, v0, v118
	v_fmac_f32_e32 v88, v0, v87
	v_bfe_u32 v123, v119, 16, 1
	v_bfe_u32 v125, v88, 16, 1
	v_add3_u32 v123, v119, v123, s53
	v_add3_u32 v125, v88, v125, s53
	v_lshrrev_b32_e32 v123, 16, v123
	v_and_or_b32 v123, v125, s52, v123
	global_store_dword v22, v123, s[4:5]
	s_waitcnt vmcnt(62)
	v_lshlrev_b32_e32 v118, 16, v89
	v_and_b32_e32 v89, 0xffff0000, v89
	v_fmac_f32_e32 v118, v0, v119
	v_fmac_f32_e32 v89, v0, v88
	v_bfe_u32 v120, v118, 16, 1
	v_bfe_u32 v124, v89, 16, 1
	v_add3_u32 v120, v118, v120, s53
	v_add3_u32 v124, v89, v124, s53
	v_lshrrev_b32_e32 v120, 16, v120
	v_and_or_b32 v120, v124, s52, v120
	global_store_dword v23, v120, s[4:5]
	s_waitcnt vmcnt(62)
	v_lshlrev_b32_e32 v119, 16, v90
	v_and_b32_e32 v90, 0xffff0000, v90
	v_fmac_f32_e32 v119, v0, v118
	v_fmac_f32_e32 v90, v0, v89
	v_bfe_u32 v121, v119, 16, 1
	v_bfe_u32 v125, v90, 16, 1
	v_add3_u32 v121, v119, v121, s53
	v_add3_u32 v125, v90, v125, s53
	v_lshrrev_b32_e32 v121, 16, v121
	v_and_or_b32 v121, v125, s52, v121
	global_store_dword v24, v121, s[4:5]
	s_waitcnt vmcnt(62)
	v_lshlrev_b32_e32 v118, 16, v91
	v_and_b32_e32 v91, 0xffff0000, v91
	v_fmac_f32_e32 v118, v0, v119
	v_fmac_f32_e32 v91, v0, v90
	v_bfe_u32 v122, v118, 16, 1
	v_bfe_u32 v124, v91, 16, 1
	v_add3_u32 v122, v118, v122, s53
	v_add3_u32 v124, v91, v124, s53
	v_lshrrev_b32_e32 v122, 16, v122
	v_and_or_b32 v122, v124, s52, v122
	global_store_dword v25, v122, s[4:5]
	s_waitcnt vmcnt(62)
	v_lshlrev_b32_e32 v119, 16, v92
	v_and_b32_e32 v92, 0xffff0000, v92
	v_fmac_f32_e32 v119, v0, v118
	v_fmac_f32_e32 v92, v0, v91
	v_bfe_u32 v123, v119, 16, 1
	v_bfe_u32 v125, v92, 16, 1
	v_add3_u32 v123, v119, v123, s53
	v_add3_u32 v125, v92, v125, s53
	v_lshrrev_b32_e32 v123, 16, v123
	v_and_or_b32 v123, v125, s52, v123
	global_store_dword v26, v123, s[4:5]
	s_waitcnt vmcnt(62)
	v_lshlrev_b32_e32 v118, 16, v93
	v_and_b32_e32 v93, 0xffff0000, v93
	v_fmac_f32_e32 v118, v0, v119
	v_fmac_f32_e32 v93, v0, v92
	v_bfe_u32 v120, v118, 16, 1
	v_bfe_u32 v124, v93, 16, 1
	v_add3_u32 v120, v118, v120, s53
	v_add3_u32 v124, v93, v124, s53
	v_lshrrev_b32_e32 v120, 16, v120
	v_and_or_b32 v120, v124, s52, v120
	global_store_dword v27, v120, s[4:5]
	s_waitcnt vmcnt(62)
	v_lshlrev_b32_e32 v119, 16, v94
	v_and_b32_e32 v94, 0xffff0000, v94
	v_fmac_f32_e32 v119, v0, v118
	v_fmac_f32_e32 v94, v0, v93
	v_bfe_u32 v121, v119, 16, 1
	v_bfe_u32 v125, v94, 16, 1
	v_add3_u32 v121, v119, v121, s53
	v_add3_u32 v125, v94, v125, s53
	v_lshrrev_b32_e32 v121, 16, v121
	v_and_or_b32 v121, v125, s52, v121
	global_store_dword v28, v121, s[4:5]
	s_waitcnt vmcnt(62)
	v_lshlrev_b32_e32 v118, 16, v95
	v_and_b32_e32 v95, 0xffff0000, v95
	v_fmac_f32_e32 v118, v0, v119
	v_fmac_f32_e32 v95, v0, v94
	v_bfe_u32 v122, v118, 16, 1
	v_bfe_u32 v124, v95, 16, 1
	v_add3_u32 v122, v118, v122, s53
	v_add3_u32 v124, v95, v124, s53
	v_lshrrev_b32_e32 v122, 16, v122
	v_and_or_b32 v122, v124, s52, v122
	global_store_dword v29, v122, s[4:5]
	s_waitcnt vmcnt(62)
	v_lshlrev_b32_e32 v119, 16, v96
	v_and_b32_e32 v96, 0xffff0000, v96
	v_fmac_f32_e32 v119, v0, v118
	v_fmac_f32_e32 v96, v0, v95
	v_bfe_u32 v123, v119, 16, 1
	v_bfe_u32 v125, v96, 16, 1
	v_add3_u32 v123, v119, v123, s53
	v_add3_u32 v125, v96, v125, s53
	v_lshrrev_b32_e32 v123, 16, v123
	v_and_or_b32 v123, v125, s52, v123
	global_store_dword v30, v123, s[4:5]
	s_waitcnt vmcnt(62)
	v_lshlrev_b32_e32 v118, 16, v97
	v_and_b32_e32 v97, 0xffff0000, v97
	v_fmac_f32_e32 v118, v0, v119
	v_fmac_f32_e32 v97, v0, v96
	v_bfe_u32 v120, v118, 16, 1
	v_bfe_u32 v124, v97, 16, 1
	v_add3_u32 v120, v118, v120, s53
	v_add3_u32 v124, v97, v124, s53
	v_lshrrev_b32_e32 v120, 16, v120
	v_and_or_b32 v120, v124, s52, v120
	global_store_dword v31, v120, s[4:5]
	s_waitcnt vmcnt(62)
	v_lshlrev_b32_e32 v119, 16, v98
	v_and_b32_e32 v98, 0xffff0000, v98
	v_fmac_f32_e32 v119, v0, v118
	v_fmac_f32_e32 v98, v0, v97
	v_bfe_u32 v121, v119, 16, 1
	v_bfe_u32 v125, v98, 16, 1
	v_add3_u32 v121, v119, v121, s53
	v_add3_u32 v125, v98, v125, s53
	v_lshrrev_b32_e32 v121, 16, v121
	v_and_or_b32 v121, v125, s52, v121
	global_store_dword v32, v121, s[4:5]
	s_waitcnt vmcnt(62)
	v_lshlrev_b32_e32 v118, 16, v99
	v_and_b32_e32 v99, 0xffff0000, v99
	v_fmac_f32_e32 v118, v0, v119
	v_fmac_f32_e32 v99, v0, v98
	v_bfe_u32 v122, v118, 16, 1
	v_bfe_u32 v124, v99, 16, 1
	v_add3_u32 v122, v118, v122, s53
	v_add3_u32 v124, v99, v124, s53
	v_lshrrev_b32_e32 v122, 16, v122
	v_and_or_b32 v122, v124, s52, v122
	global_store_dword v33, v122, s[4:5]
	s_waitcnt vmcnt(62)
	v_lshlrev_b32_e32 v119, 16, v100
	v_and_b32_e32 v100, 0xffff0000, v100
	v_fmac_f32_e32 v119, v0, v118
	v_fmac_f32_e32 v100, v0, v99
	v_bfe_u32 v123, v119, 16, 1
	v_bfe_u32 v125, v100, 16, 1
	v_add3_u32 v123, v119, v123, s53
	v_add3_u32 v125, v100, v125, s53
	v_lshrrev_b32_e32 v123, 16, v123
	v_and_or_b32 v123, v125, s52, v123
	global_store_dword v34, v123, s[4:5]
	s_waitcnt vmcnt(62)
	v_lshlrev_b32_e32 v118, 16, v101
	v_and_b32_e32 v101, 0xffff0000, v101
	v_fmac_f32_e32 v118, v0, v119
	v_fmac_f32_e32 v101, v0, v100
	v_bfe_u32 v120, v118, 16, 1
	v_bfe_u32 v124, v101, 16, 1
	v_add3_u32 v120, v118, v120, s53
	v_add3_u32 v124, v101, v124, s53
	v_lshrrev_b32_e32 v120, 16, v120
	v_and_or_b32 v120, v124, s52, v120
	global_store_dword v35, v120, s[4:5]
	s_waitcnt vmcnt(62)
	v_lshlrev_b32_e32 v119, 16, v102
	v_and_b32_e32 v102, 0xffff0000, v102
	v_fmac_f32_e32 v119, v0, v118
	v_fmac_f32_e32 v102, v0, v101
	v_bfe_u32 v121, v119, 16, 1
	v_bfe_u32 v125, v102, 16, 1
	v_add3_u32 v121, v119, v121, s53
	v_add3_u32 v125, v102, v125, s53
	v_lshrrev_b32_e32 v121, 16, v121
	v_and_or_b32 v121, v125, s52, v121
	global_store_dword v36, v121, s[4:5]
	s_waitcnt vmcnt(62)
	v_lshlrev_b32_e32 v118, 16, v103
	v_and_b32_e32 v103, 0xffff0000, v103
	v_fmac_f32_e32 v118, v0, v119
	v_fmac_f32_e32 v103, v0, v102
	v_bfe_u32 v122, v118, 16, 1
	v_bfe_u32 v124, v103, 16, 1
	v_add3_u32 v122, v118, v122, s53
	v_add3_u32 v124, v103, v124, s53
	v_lshrrev_b32_e32 v122, 16, v122
	v_and_or_b32 v122, v124, s52, v122
	global_store_dword v37, v122, s[4:5]
	s_waitcnt vmcnt(62)
	v_lshlrev_b32_e32 v126, 16, v38
	v_and_b32_e32 v38, 0xffff0000, v38
	v_fmac_f32_e32 v126, 0, v0
	v_fmac_f32_e32 v38, 0, v0
	v_bfe_u32 v140, v126, 16, 1
	v_bfe_u32 v144, v38, 16, 1
	v_add3_u32 v140, v126, v140, s53
	v_add3_u32 v144, v38, v144, s53
	v_lshrrev_b32_e32 v140, 16, v140
	v_and_or_b32 v140, v144, s52, v140
	global_store_dword v7, v140, s[6:7]
	global_store_dword v6, v1, s[6:7]
	s_waitcnt vmcnt(63)
	v_lshlrev_b32_e32 v127, 16, v39
	v_and_b32_e32 v39, 0xffff0000, v39
	v_fmac_f32_e32 v127, v0, v126
	v_fmac_f32_e32 v39, v0, v38
	v_bfe_u32 v141, v127, 16, 1
	v_bfe_u32 v145, v39, 16, 1
	v_add3_u32 v141, v127, v141, s53
	v_add3_u32 v145, v39, v145, s53
	v_lshrrev_b32_e32 v141, 16, v141
	v_and_or_b32 v141, v145, s52, v141
	global_store_dword v8, v141, s[6:7]
	s_waitcnt vmcnt(63)
	v_lshlrev_b32_e32 v126, 16, v40
	v_and_b32_e32 v40, 0xffff0000, v40
	v_fmac_f32_e32 v126, v0, v127
	v_fmac_f32_e32 v40, v0, v39
	v_bfe_u32 v142, v126, 16, 1
	v_bfe_u32 v144, v40, 16, 1
	v_add3_u32 v142, v126, v142, s53
	v_add3_u32 v144, v40, v144, s53
	v_lshrrev_b32_e32 v142, 16, v142
	v_and_or_b32 v142, v144, s52, v142
	global_store_dword v9, v142, s[6:7]
	s_waitcnt vmcnt(63)
	v_lshlrev_b32_e32 v127, 16, v41
	v_and_b32_e32 v41, 0xffff0000, v41
	v_fmac_f32_e32 v127, v0, v126
	v_fmac_f32_e32 v41, v0, v40
	v_bfe_u32 v143, v127, 16, 1
	v_bfe_u32 v145, v41, 16, 1
	v_add3_u32 v143, v127, v143, s53
	v_add3_u32 v145, v41, v145, s53
	v_lshrrev_b32_e32 v143, 16, v143
	v_and_or_b32 v143, v145, s52, v143
	global_store_dword v10, v143, s[6:7]
	s_waitcnt vmcnt(63)
	v_lshlrev_b32_e32 v126, 16, v42
	v_and_b32_e32 v42, 0xffff0000, v42
	v_fmac_f32_e32 v126, v0, v127
	v_fmac_f32_e32 v42, v0, v41
	v_bfe_u32 v140, v126, 16, 1
	v_bfe_u32 v144, v42, 16, 1
	v_add3_u32 v140, v126, v140, s53
	v_add3_u32 v144, v42, v144, s53
	v_lshrrev_b32_e32 v140, 16, v140
	v_and_or_b32 v140, v144, s52, v140
	global_store_dword v11, v140, s[6:7]
	s_waitcnt vmcnt(63)
	v_lshlrev_b32_e32 v127, 16, v43
	v_and_b32_e32 v43, 0xffff0000, v43
	v_fmac_f32_e32 v127, v0, v126
	v_fmac_f32_e32 v43, v0, v42
	v_bfe_u32 v141, v127, 16, 1
	v_bfe_u32 v145, v43, 16, 1
	v_add3_u32 v141, v127, v141, s53
	v_add3_u32 v145, v43, v145, s53
	v_lshrrev_b32_e32 v141, 16, v141
	v_and_or_b32 v141, v145, s52, v141
	global_store_dword v12, v141, s[6:7]
	s_waitcnt vmcnt(63)
	v_lshlrev_b32_e32 v126, 16, v44
	v_and_b32_e32 v44, 0xffff0000, v44
	v_fmac_f32_e32 v126, v0, v127
	v_fmac_f32_e32 v44, v0, v43
	v_bfe_u32 v142, v126, 16, 1
	v_bfe_u32 v144, v44, 16, 1
	v_add3_u32 v142, v126, v142, s53
	v_add3_u32 v144, v44, v144, s53
	v_lshrrev_b32_e32 v142, 16, v142
	v_and_or_b32 v142, v144, s52, v142
	global_store_dword v13, v142, s[6:7]
	s_waitcnt vmcnt(63)
	v_lshlrev_b32_e32 v127, 16, v45
	v_and_b32_e32 v45, 0xffff0000, v45
	v_fmac_f32_e32 v127, v0, v126
	v_fmac_f32_e32 v45, v0, v44
	v_bfe_u32 v143, v127, 16, 1
	v_bfe_u32 v145, v45, 16, 1
	v_add3_u32 v143, v127, v143, s53
	v_add3_u32 v145, v45, v145, s53
	v_lshrrev_b32_e32 v143, 16, v143
	v_and_or_b32 v143, v145, s52, v143
	global_store_dword v14, v143, s[6:7]
	s_waitcnt vmcnt(63)
	v_lshlrev_b32_e32 v126, 16, v46
	v_and_b32_e32 v46, 0xffff0000, v46
	v_fmac_f32_e32 v126, v0, v127
	v_fmac_f32_e32 v46, v0, v45
	v_bfe_u32 v140, v126, 16, 1
	v_bfe_u32 v144, v46, 16, 1
	v_add3_u32 v140, v126, v140, s53
	v_add3_u32 v144, v46, v144, s53
	v_lshrrev_b32_e32 v140, 16, v140
	v_and_or_b32 v140, v144, s52, v140
	global_store_dword v15, v140, s[6:7]
	s_waitcnt vmcnt(63)
	v_lshlrev_b32_e32 v127, 16, v47
	v_and_b32_e32 v47, 0xffff0000, v47
	v_fmac_f32_e32 v127, v0, v126
	v_fmac_f32_e32 v47, v0, v46
	v_bfe_u32 v141, v127, 16, 1
	v_bfe_u32 v145, v47, 16, 1
	v_add3_u32 v141, v127, v141, s53
	v_add3_u32 v145, v47, v145, s53
	v_lshrrev_b32_e32 v141, 16, v141
	v_and_or_b32 v141, v145, s52, v141
	global_store_dword v16, v141, s[6:7]
	s_waitcnt vmcnt(63)
	v_lshlrev_b32_e32 v126, 16, v48
	v_and_b32_e32 v48, 0xffff0000, v48
	v_fmac_f32_e32 v126, v0, v127
	v_fmac_f32_e32 v48, v0, v47
	v_bfe_u32 v142, v126, 16, 1
	v_bfe_u32 v144, v48, 16, 1
	v_add3_u32 v142, v126, v142, s53
	v_add3_u32 v144, v48, v144, s53
	v_lshrrev_b32_e32 v142, 16, v142
	v_and_or_b32 v142, v144, s52, v142
	global_store_dword v17, v142, s[6:7]
	s_waitcnt vmcnt(63)
	v_lshlrev_b32_e32 v127, 16, v49
	v_and_b32_e32 v49, 0xffff0000, v49
	v_fmac_f32_e32 v127, v0, v126
	v_fmac_f32_e32 v49, v0, v48
	v_bfe_u32 v143, v127, 16, 1
	v_bfe_u32 v145, v49, 16, 1
	v_add3_u32 v143, v127, v143, s53
	v_add3_u32 v145, v49, v145, s53
	v_lshrrev_b32_e32 v143, 16, v143
	v_and_or_b32 v143, v145, s52, v143
	global_store_dword v18, v143, s[6:7]
	s_waitcnt vmcnt(63)
	v_lshlrev_b32_e32 v126, 16, v50
	v_and_b32_e32 v50, 0xffff0000, v50
	v_fmac_f32_e32 v126, v0, v127
	v_fmac_f32_e32 v50, v0, v49
	v_bfe_u32 v140, v126, 16, 1
	v_bfe_u32 v144, v50, 16, 1
	v_add3_u32 v140, v126, v140, s53
	v_add3_u32 v144, v50, v144, s53
	v_lshrrev_b32_e32 v140, 16, v140
	v_and_or_b32 v140, v144, s52, v140
	global_store_dword v19, v140, s[6:7]
	s_waitcnt vmcnt(63)
	v_lshlrev_b32_e32 v127, 16, v51
	v_and_b32_e32 v51, 0xffff0000, v51
	v_fmac_f32_e32 v127, v0, v126
	v_fmac_f32_e32 v51, v0, v50
	v_bfe_u32 v141, v127, 16, 1
	v_bfe_u32 v145, v51, 16, 1
	v_add3_u32 v141, v127, v141, s53
	v_add3_u32 v145, v51, v145, s53
	v_lshrrev_b32_e32 v141, 16, v141
	v_and_or_b32 v141, v145, s52, v141
	global_store_dword v20, v141, s[6:7]
	s_waitcnt vmcnt(63)
	v_lshlrev_b32_e32 v126, 16, v52
	v_and_b32_e32 v52, 0xffff0000, v52
	v_fmac_f32_e32 v126, v0, v127
	v_fmac_f32_e32 v52, v0, v51
	v_bfe_u32 v142, v126, 16, 1
	v_bfe_u32 v144, v52, 16, 1
	v_add3_u32 v142, v126, v142, s53
	v_add3_u32 v144, v52, v144, s53
	v_lshrrev_b32_e32 v142, 16, v142
	v_and_or_b32 v142, v144, s52, v142
	global_store_dword v21, v142, s[6:7]
	s_waitcnt vmcnt(63)
	v_lshlrev_b32_e32 v127, 16, v53
	v_and_b32_e32 v53, 0xffff0000, v53
	v_fmac_f32_e32 v127, v0, v126
	v_fmac_f32_e32 v53, v0, v52
	v_bfe_u32 v143, v127, 16, 1
	v_bfe_u32 v145, v53, 16, 1
	v_add3_u32 v143, v127, v143, s53
	v_add3_u32 v145, v53, v145, s53
	v_lshrrev_b32_e32 v143, 16, v143
	v_and_or_b32 v143, v145, s52, v143
	global_store_dword v22, v143, s[6:7]
	s_waitcnt vmcnt(63)
	v_lshlrev_b32_e32 v126, 16, v54
	v_and_b32_e32 v54, 0xffff0000, v54
	v_fmac_f32_e32 v126, v0, v127
	v_fmac_f32_e32 v54, v0, v53
	v_bfe_u32 v140, v126, 16, 1
	v_bfe_u32 v144, v54, 16, 1
	v_add3_u32 v140, v126, v140, s53
	v_add3_u32 v144, v54, v144, s53
	v_lshrrev_b32_e32 v140, 16, v140
	v_and_or_b32 v140, v144, s52, v140
	global_store_dword v23, v140, s[6:7]
	s_waitcnt vmcnt(63)
	v_lshlrev_b32_e32 v127, 16, v55
	v_and_b32_e32 v55, 0xffff0000, v55
	v_fmac_f32_e32 v127, v0, v126
	v_fmac_f32_e32 v55, v0, v54
	v_bfe_u32 v141, v127, 16, 1
	v_bfe_u32 v145, v55, 16, 1
	v_add3_u32 v141, v127, v141, s53
	v_add3_u32 v145, v55, v145, s53
	v_lshrrev_b32_e32 v141, 16, v141
	v_and_or_b32 v141, v145, s52, v141
	global_store_dword v24, v141, s[6:7]
	s_waitcnt vmcnt(63)
	v_lshlrev_b32_e32 v126, 16, v56
	v_and_b32_e32 v56, 0xffff0000, v56
	v_fmac_f32_e32 v126, v0, v127
	v_fmac_f32_e32 v56, v0, v55
	v_bfe_u32 v142, v126, 16, 1
	v_bfe_u32 v144, v56, 16, 1
	v_add3_u32 v142, v126, v142, s53
	v_add3_u32 v144, v56, v144, s53
	v_lshrrev_b32_e32 v142, 16, v142
	v_and_or_b32 v142, v144, s52, v142
	global_store_dword v25, v142, s[6:7]
	s_waitcnt vmcnt(63)
	v_lshlrev_b32_e32 v127, 16, v57
	v_and_b32_e32 v57, 0xffff0000, v57
	v_fmac_f32_e32 v127, v0, v126
	v_fmac_f32_e32 v57, v0, v56
	v_bfe_u32 v143, v127, 16, 1
	v_bfe_u32 v145, v57, 16, 1
	v_add3_u32 v143, v127, v143, s53
	v_add3_u32 v145, v57, v145, s53
	v_lshrrev_b32_e32 v143, 16, v143
	v_and_or_b32 v143, v145, s52, v143
	global_store_dword v26, v143, s[6:7]
	s_waitcnt vmcnt(63)
	v_lshlrev_b32_e32 v126, 16, v58
	v_and_b32_e32 v58, 0xffff0000, v58
	v_fmac_f32_e32 v126, v0, v127
	v_fmac_f32_e32 v58, v0, v57
	v_bfe_u32 v140, v126, 16, 1
	v_bfe_u32 v144, v58, 16, 1
	v_add3_u32 v140, v126, v140, s53
	v_add3_u32 v144, v58, v144, s53
	v_lshrrev_b32_e32 v140, 16, v140
	v_and_or_b32 v140, v144, s52, v140
	global_store_dword v27, v140, s[6:7]
	s_waitcnt vmcnt(63)
	v_lshlrev_b32_e32 v127, 16, v59
	v_and_b32_e32 v59, 0xffff0000, v59
	v_fmac_f32_e32 v127, v0, v126
	v_fmac_f32_e32 v59, v0, v58
	v_bfe_u32 v141, v127, 16, 1
	v_bfe_u32 v145, v59, 16, 1
	v_add3_u32 v141, v127, v141, s53
	v_add3_u32 v145, v59, v145, s53
	v_lshrrev_b32_e32 v141, 16, v141
	v_and_or_b32 v141, v145, s52, v141
	global_store_dword v28, v141, s[6:7]
	s_waitcnt vmcnt(63)
	v_lshlrev_b32_e32 v126, 16, v60
	v_and_b32_e32 v60, 0xffff0000, v60
	v_fmac_f32_e32 v126, v0, v127
	v_fmac_f32_e32 v60, v0, v59
	v_bfe_u32 v142, v126, 16, 1
	v_bfe_u32 v144, v60, 16, 1
	v_add3_u32 v142, v126, v142, s53
	v_add3_u32 v144, v60, v144, s53
	v_lshrrev_b32_e32 v142, 16, v142
	v_and_or_b32 v142, v144, s52, v142
	global_store_dword v29, v142, s[6:7]
	s_waitcnt vmcnt(63)
	v_lshlrev_b32_e32 v127, 16, v61
	v_and_b32_e32 v61, 0xffff0000, v61
	v_fmac_f32_e32 v127, v0, v126
	v_fmac_f32_e32 v61, v0, v60
	v_bfe_u32 v143, v127, 16, 1
	v_bfe_u32 v145, v61, 16, 1
	v_add3_u32 v143, v127, v143, s53
	v_add3_u32 v145, v61, v145, s53
	v_lshrrev_b32_e32 v143, 16, v143
	v_and_or_b32 v143, v145, s52, v143
	global_store_dword v30, v143, s[6:7]
	s_waitcnt vmcnt(63)
	v_lshlrev_b32_e32 v126, 16, v62
	v_and_b32_e32 v62, 0xffff0000, v62
	v_fmac_f32_e32 v126, v0, v127
	v_fmac_f32_e32 v62, v0, v61
	v_bfe_u32 v140, v126, 16, 1
	v_bfe_u32 v144, v62, 16, 1
	v_add3_u32 v140, v126, v140, s53
	v_add3_u32 v144, v62, v144, s53
	v_lshrrev_b32_e32 v140, 16, v140
	v_and_or_b32 v140, v144, s52, v140
	global_store_dword v31, v140, s[6:7]
	s_waitcnt vmcnt(63)
	v_lshlrev_b32_e32 v127, 16, v63
	v_and_b32_e32 v63, 0xffff0000, v63
	v_fmac_f32_e32 v127, v0, v126
	v_fmac_f32_e32 v63, v0, v62
	v_bfe_u32 v141, v127, 16, 1
	v_bfe_u32 v145, v63, 16, 1
	v_add3_u32 v141, v127, v141, s53
	v_add3_u32 v145, v63, v145, s53
	v_lshrrev_b32_e32 v141, 16, v141
	v_and_or_b32 v141, v145, s52, v141
	global_store_dword v32, v141, s[6:7]
	s_waitcnt vmcnt(63)
	v_lshlrev_b32_e32 v126, 16, v113
	v_and_b32_e32 v113, 0xffff0000, v113
	v_fmac_f32_e32 v126, v0, v127
	v_fmac_f32_e32 v113, v0, v63
	v_bfe_u32 v142, v126, 16, 1
	v_bfe_u32 v144, v113, 16, 1
	v_add3_u32 v142, v126, v142, s53
	v_add3_u32 v144, v113, v144, s53
	v_lshrrev_b32_e32 v142, 16, v142
	v_and_or_b32 v142, v144, s52, v142
	global_store_dword v33, v142, s[6:7]
	s_waitcnt vmcnt(63)
	v_lshlrev_b32_e32 v127, 16, v114
	v_and_b32_e32 v114, 0xffff0000, v114
	v_fmac_f32_e32 v127, v0, v126
	v_fmac_f32_e32 v114, v0, v113
	v_bfe_u32 v143, v127, 16, 1
	v_bfe_u32 v145, v114, 16, 1
	v_add3_u32 v143, v127, v143, s53
	v_add3_u32 v145, v114, v145, s53
	v_lshrrev_b32_e32 v143, 16, v143
	v_and_or_b32 v143, v145, s52, v143
	global_store_dword v34, v143, s[6:7]
	s_waitcnt vmcnt(63)
	v_lshlrev_b32_e32 v126, 16, v115
	v_and_b32_e32 v115, 0xffff0000, v115
	v_fmac_f32_e32 v126, v0, v127
	v_fmac_f32_e32 v115, v0, v114
	v_bfe_u32 v140, v126, 16, 1
	v_bfe_u32 v144, v115, 16, 1
	v_add3_u32 v140, v126, v140, s53
	v_add3_u32 v144, v115, v144, s53
	v_lshrrev_b32_e32 v140, 16, v140
	v_and_or_b32 v140, v144, s52, v140
	global_store_dword v35, v140, s[6:7]
	s_waitcnt vmcnt(63)
	v_lshlrev_b32_e32 v127, 16, v116
	v_and_b32_e32 v116, 0xffff0000, v116
	v_fmac_f32_e32 v127, v0, v126
	v_fmac_f32_e32 v116, v0, v115
	v_bfe_u32 v141, v127, 16, 1
	v_bfe_u32 v145, v116, 16, 1
	v_add3_u32 v141, v127, v141, s53
	v_add3_u32 v145, v116, v145, s53
	v_lshrrev_b32_e32 v141, 16, v141
	v_and_or_b32 v141, v145, s52, v141
	global_store_dword v36, v141, s[6:7]
	s_waitcnt vmcnt(63)
	v_lshlrev_b32_e32 v126, 16, v117
	v_and_b32_e32 v117, 0xffff0000, v117
	v_fmac_f32_e32 v126, v0, v127
	v_fmac_f32_e32 v117, v0, v116
	v_bfe_u32 v142, v126, 16, 1
	v_bfe_u32 v144, v117, 16, 1
	v_add3_u32 v142, v126, v142, s53
	v_add3_u32 v144, v117, v144, s53
	v_lshrrev_b32_e32 v142, 16, v142
	v_and_or_b32 v142, v144, s52, v142
	global_store_dword v37, v142, s[6:7]
	s_branch .LBB0_570
